# g7 plus k_da data loads of phase_odd_rows issued at the row top (unconditional, into spare registers) instead of inside the rope section
# baseline (speedup 1.0000x reference)
; __device__ __forceinline__ unsigned pk2(float lo, float hi) { unsigned r; asm("v_cvt_pk_bf16_f32 %0, %1, %2" : "=v"(r) : "v"(lo), "v"(hi)); return r; }
; __device__ __forceinline__ float bflo(unsigned u) { return __uint_as_float(u << 16); }
; __device__ __forceinline__ float bfhi(unsigned u) { return __uint_as_float(u & 0xffff0000u); }
; __device__ __forceinline__ void phase_odd_rows(const Params& p, int o, int grp) {
;     ...
;         {
;             u32x4 v = {0u, 0u, 0u, 0u}; if (lane < 48) v = *(const u32x4*)(ur + 2048 + lane * 8);
;             float x[8] = {bflo(v.x), bfhi(v.x), bflo(v.y), bfhi(v.y), bflo(v.z), bfhi(v.z), bflo(v.w), bfhi(v.w)};
;             float ss = 0.f;
; #pragma unroll
;             for (int j = 0; j < 8; ++j) ss += x[j] * x[j];
;             const float r = rsqrtf(wave_sum(ss) * (1.f / 384.f) + EPS);
;             if (lane < 48) { u32x4 ov; ov.x = pk2(x[0] * r * gqa[0], x[1] * r * gqa[1]); ov.y = pk2(x[2] * r * gqa[2], x[3] * r * gqa[3]); ov.z = pk2(x[4] * r * gqb[0], x[5] * r * gqb[1]); ov.w = pk2(x[6] * r * gqb[2], x[7] * r * gqb[3]);
;                 *(u32x4*)(ur + 2048 + lane * 8) = ov; }
;         }
;     ...
;             const int cmb = lane >> 1, hf = lane & 1, ax = cmb & 1, i1 = 1024 + (cmb >> 1) * 64 + ax * 32 + 8 * hf;
;             const u32x4 a = *(const u32x4*)(ur + i1), bq = *(const u32x4*)(ur + i1 + 16);
.LBB0_571:
	s_or_b64 exec, exec, s[12:13]
	v_mov_b32_e32 v68, 0
	v_mov_b32_e32 v69, 0
	v_mov_b32_e32 v70, 0
	v_mov_b32_e32 v71, 0
	s_and_saveexec_b64 s[12:13], s[4:5]
	v_add_co_u32_e32 v72, vcc, 0x13ad9000, v20
	s_nop 1
	v_addc_co_u32_e32 v73, vcc, 0, v21, vcc
	global_load_dwordx4 v[68:71], v[72:73], off offset:2560
	s_or_b64 exec, exec, s[12:13]
	v_lshl_add_u64 v[86:87], v[26:27], 0, s[16:17]
	v_add_co_u32_e32 v86, vcc, 0x13ad8000, v86
	s_nop 1
	v_addc_co_u32_e32 v87, vcc, 0, v87, vcc
	global_load_dwordx4 v[96:99], v[86:87], off offset:3840
	global_load_dwordx4 v[100:103], v[86:87], off offset:3872
	s_waitcnt vmcnt(3)
	v_and_b32_e32 v33, 0xffff0000, v16
	v_lshlrev_b32_e32 v42, 16, v16
	v_lshlrev_b32_e32 v32, 16, v17
	v_and_b32_e32 v23, 0xffff0000, v17
	v_lshlrev_b32_e32 v17, 16, v19
	v_and_b32_e32 v16, 0xffff0000, v19
	v_mul_f32_e32 v19, v33, v33
	v_fmac_f32_e32 v19, v42, v42
	v_fmac_f32_e32 v19, v32, v32
	v_lshlrev_b32_e32 v22, 16, v18
	v_fmac_f32_e32 v19, v23, v23
	v_and_b32_e32 v18, 0xffff0000, v18
	v_fmac_f32_e32 v19, v22, v22
	v_fmac_f32_e32 v19, v18, v18
	v_fmac_f32_e32 v19, v17, v17
	v_fmac_f32_e32 v19, v16, v16
	ds_bpermute_b32 v43, v35, v19
	s_waitcnt lgkmcnt(0)
	v_add_f32_e32 v19, v19, v43
	ds_bpermute_b32 v43, v36, v19
	s_waitcnt lgkmcnt(0)
	v_add_f32_e32 v19, v19, v43
	ds_bpermute_b32 v43, v37, v19
	s_waitcnt lgkmcnt(0)
	v_add_f32_e32 v19, v19, v43
	ds_bpermute_b32 v43, v38, v19
	s_waitcnt lgkmcnt(0)
	v_add_f32_e32 v19, v19, v43
	ds_bpermute_b32 v43, v39, v19
	s_waitcnt lgkmcnt(0)
	v_add_f32_e32 v19, v19, v43
	ds_bpermute_b32 v43, v40, v19
	s_and_saveexec_b64 s[12:13], s[0:1]
	s_cbranch_execz .LBB0_573
	s_waitcnt lgkmcnt(0)
	v_add_f32_e32 v19, v19, v43
	v_fmamk_f32 v19, v19, 0x3b2aaaab, v195
	v_mul_f32_e32 v43, 0x4b800000, v19
	v_cmp_gt_f32_e32 vcc, s41, v19
	s_nop 1
	v_cndmask_b32_e32 v19, v19, v43, vcc
	v_rsq_f32_e32 v19, v19
	s_nop 0
	v_mul_f32_e32 v43, 0x45800000, v19
	v_cndmask_b32_e32 v19, v19, v43, vcc
	v_mul_f32_e32 v16, v19, v16
	v_mul_f32_e32 v17, v19, v17
	v_mul_f32_e32 v16, v11, v16
	v_mul_f32_e32 v42, v19, v42
	v_mul_f32_e32 v17, v10, v17
	v_cvt_pk_bf16_f32 v45, v17, v16
	v_add_co_u32_e32 v16, vcc, 0x13ad9000, v20
	v_mul_f32_e32 v33, v19, v33
	v_mul_f32_e32 v42, v4, v42
	v_mul_f32_e32 v32, v19, v32
	v_mul_f32_e32 v23, v19, v23
	v_mul_f32_e32 v22, v19, v22
	v_mul_f32_e32 v18, v19, v18
	v_addc_co_u32_e32 v17, vcc, 0, v21, vcc
	v_mul_f32_e32 v33, v5, v33
	v_cvt_pk_bf16_f32 v42, v42, v33
	v_mul_f32_e32 v32, v6, v32
	v_mul_f32_e32 v23, v7, v23
	v_cvt_pk_bf16_f32 v43, v32, v23
	v_mul_f32_e32 v22, v8, v22
	v_mul_f32_e32 v18, v9, v18
	v_cvt_pk_bf16_f32 v44, v22, v18
	global_store_dwordx4 v[16:17], v[42:45], off offset:1792

; __device__ __forceinline__ unsigned pk2(float lo, float hi) { unsigned r; asm("v_cvt_pk_bf16_f32 %0, %1, %2" : "=v"(r) : "v"(lo), "v"(hi)); return r; }
; __device__ __forceinline__ float bflo(unsigned u) { return __uint_as_float(u << 16); }
; __device__ __forceinline__ float bfhi(unsigned u) { return __uint_as_float(u & 0xffff0000u); }
; __device__ __forceinline__ void phase_odd_rows(const Params& p, int o, int grp) {
;     ...
;         if (lat) {
;             const int cmb = lane >> 1, hf = lane & 1, ax = cmb & 1, i1 = 1024 + (cmb >> 1) * 64 + ax * 32 + 8 * hf;
;             const u32x4 a = *(const u32x4*)(ur + i1), bq = *(const u32x4*)(ur + i1 + 16);
;             const float* tp = rt + ((ax ? pcol : prow) * 16 + 8 * hf) * 2;
;             u32x4 oa, ob;
; #pragma unroll
;             for (int q = 0; q < 4; ++q) {
;                 const f32x4 cs = *(const f32x4*)(tp + 4 * q);
;                 const float x1a = bflo(a[q]), x1b = bfhi(a[q]), x2a = bflo(bq[q]), x2b = bfhi(bq[q]);
;                 oa[q] = pk2(x1a * cs[0] - x2a * cs[1], x1b * cs[2] - x2b * cs[3]);
;                 ob[q] = pk2(x2a * cs[0] + x1a * cs[1], x2b * cs[2] + x1b * cs[3]);
;             }
;             *(u32x4*)(ur + i1) = oa; *(u32x4*)(ur + i1 + 16) = ob;
;         }
.LBB0_577:
	s_or_b64 exec, exec, s[12:13]
	s_mov_b32 s3, 0x3e0f83e1
	v_mul_hi_i32 v16, v34, s3
	v_lshrrev_b32_e32 v17, 31, v16
	v_ashrrev_i32_e32 v16, 11, v16
	v_add_u32_e32 v16, v16, v17
	v_mul_i32_i24_e32 v16, 0x2100, v16
	v_sub_u32_e32 v16, v34, v16
	s_movk_i32 s3, 0x100
	v_cmp_gt_i32_e64 s[12:13], s3, v16
	s_movk_i32 s3, 0xff
	v_add_u32_e32 v17, 0xffffff00, v16
	v_cmp_lt_i32_e32 vcc, s3, v16
	s_waitcnt lgkmcnt(0)
	v_ashrrev_i32_e32 v43, 6, v17
	v_and_b32_e32 v42, 63, v16
	s_and_saveexec_b64 s[34:35], vcc
	s_cbranch_execz .LBB0_579
	v_lshl_add_u64 v[16:17], v[26:27], 0, s[16:17]
	v_cndmask_b32_e64 v44, v42, v43, s[6:7]
	v_add_co_u32_e32 v32, vcc, 0x13ad8000, v16
	v_lshl_or_b32 v44, v44, 5, v41
	s_nop 0
	v_addc_co_u32_e32 v33, vcc, 0, v17, vcc
	v_ashrrev_i32_e32 v45, 31, v44
	v_mov_b64_e32 v[16:17], v[96:97]
	v_mov_b64_e32 v[18:19], v[98:99]
	v_mov_b64_e32 v[20:21], v[100:101]
	v_mov_b64_e32 v[22:23], v[102:103]
	v_lshl_add_u64 v[48:49], v[44:45], 2, s[64:65]
	global_load_dwordx4 v[44:47], v[48:49], off
	global_load_dwordx4 v[56:59], v[48:49], off offset:16
	global_load_dwordx4 v[60:63], v[48:49], off offset:32
	global_load_dwordx4 v[64:67], v[48:49], off offset:48
	v_lshlrev_b32_e32 v51, 16, v16
	v_lshlrev_b32_e32 v50, 16, v20
	s_waitcnt vmcnt(3)
	v_pk_mul_f32 v[52:53], v[44:45], v[50:51] op_sel:[0,1] op_sel_hi:[1,0]
	v_pk_mul_f32 v[44:45], v[44:45], v[50:51]
	v_sub_f32_e32 v52, v52, v53
	v_add_f32_e32 v53, v45, v44
	v_and_b32_e32 v45, 0xffff0000, v16
	v_and_b32_e32 v44, 0xffff0000, v20
	v_pk_mul_f32 v[50:51], v[46:47], v[44:45] op_sel:[0,1] op_sel_hi:[1,0]
	v_pk_mul_f32 v[44:45], v[46:47], v[44:45]
	v_sub_f32_e32 v16, v50, v51
	v_add_f32_e32 v20, v45, v44
	v_lshlrev_b32_e32 v51, 16, v17
	v_lshlrev_b32_e32 v50, 16, v21
	v_cvt_pk_bf16_f32 v16, v52, v16
	v_cvt_pk_bf16_f32 v20, v53, v20
	s_waitcnt vmcnt(2)
	v_mov_b64_e32 v[44:45], v[56:57]
	v_mov_b64_e32 v[46:47], v[58:59]
	v_pk_mul_f32 v[52:53], v[44:45], v[50:51] op_sel:[0,1] op_sel_hi:[1,0]
	v_pk_mul_f32 v[44:45], v[44:45], v[50:51]
	v_sub_f32_e32 v52, v52, v53
	v_add_f32_e32 v53, v44, v45
	v_and_b32_e32 v45, 0xffff0000, v17
	v_and_b32_e32 v44, 0xffff0000, v21
	v_pk_mul_f32 v[50:51], v[46:47], v[44:45] op_sel:[0,1] op_sel_hi:[1,0]
	v_pk_mul_f32 v[44:45], v[46:47], v[44:45]
	v_sub_f32_e32 v17, v50, v51
	v_add_f32_e32 v21, v44, v45
	v_lshlrev_b32_e32 v51, 16, v18
	v_lshlrev_b32_e32 v50, 16, v22
	v_cvt_pk_bf16_f32 v17, v52, v17
	v_cvt_pk_bf16_f32 v21, v53, v21
	s_waitcnt vmcnt(1)
	v_mov_b64_e32 v[44:45], v[60:61]
	v_mov_b64_e32 v[46:47], v[62:63]
	v_pk_mul_f32 v[52:53], v[44:45], v[50:51] op_sel:[0,1] op_sel_hi:[1,0]
	v_pk_mul_f32 v[44:45], v[44:45], v[50:51]
	v_sub_f32_e32 v52, v52, v53
	v_add_f32_e32 v53, v44, v45
	v_and_b32_e32 v45, 0xffff0000, v18
	v_and_b32_e32 v44, 0xffff0000, v22
	v_pk_mul_f32 v[50:51], v[46:47], v[44:45] op_sel:[0,1] op_sel_hi:[1,0]
	v_pk_mul_f32 v[44:45], v[46:47], v[44:45]
	v_sub_f32_e32 v18, v50, v51
	v_add_f32_e32 v22, v44, v45
	v_lshlrev_b32_e32 v49, 16, v19
	v_lshlrev_b32_e32 v48, 16, v23
	v_cvt_pk_bf16_f32 v18, v52, v18
	v_cvt_pk_bf16_f32 v22, v53, v22
	s_waitcnt vmcnt(0)
	v_mov_b64_e32 v[44:45], v[64:65]
	v_mov_b64_e32 v[46:47], v[66:67]
	v_pk_mul_f32 v[50:51], v[44:45], v[48:49] op_sel:[0,1] op_sel_hi:[1,0]
	v_pk_mul_f32 v[44:45], v[44:45], v[48:49]
	v_sub_f32_e32 v50, v50, v51
	v_add_f32_e32 v51, v44, v45
	v_and_b32_e32 v45, 0xffff0000, v19
	v_and_b32_e32 v44, 0xffff0000, v23
	v_pk_mul_f32 v[48:49], v[46:47], v[44:45] op_sel:[0,1] op_sel_hi:[1,0]
	v_pk_mul_f32 v[44:45], v[46:47], v[44:45]
	v_sub_f32_e32 v19, v48, v49
	v_cvt_pk_bf16_f32 v19, v50, v19
	v_add_f32_e32 v23, v44, v45
	v_cvt_pk_bf16_f32 v23, v51, v23
	global_store_dwordx4 v[32:33], v[16:19], off offset:3840
	global_store_dwordx4 v[32:33], v[20:23], off offset:3872
